# x3 gelu epilogue restructured: 4 elements in lockstep (no dependent trans chains), counted vmcnt
# baseline (speedup 1.0000x reference)
.LBB0_153:
	global_load_dwordx4 v[76:79], v[134:135], off
	global_load_dwordx4 v[96:99], v[134:135], off offset:192
	v_add_u32_e32 v0, v179, v162
	s_waitcnt vmcnt(6)
	ds_read_b128 v[44:47], v0 offset:33280
	v_add_u32_e32 v148, s12, v192
	v_or_b32_e32 v203, 1, v148
	v_or_b32_e32 v202, 2, v148
	v_or_b32_e32 v201, 3, v148
	v_or_b32_e32 v200, 4, v148
	v_or_b32_e32 v199, 5, v148
	v_or_b32_e32 v198, 6, v148
	v_or_b32_e32 v197, 7, v148
	v_or_b32_e32 v196, 8, v148
	v_or_b32_e32 v195, 9, v148
	v_or_b32_e32 v194, 10, v148
	v_or_b32_e32 v193, 11, v148
	v_or_b32_e32 v123, 12, v148
	v_or_b32_e32 v121, 13, v148
	v_or_b32_e32 v103, 14, v148
	v_or_b32_e32 v102, 15, v148
	s_add_i32 s11, s11, 1
	v_add_u32_e32 v119, 0x2000, v119
	s_cmp_eq_u32 s11, 4
	s_waitcnt vmcnt(1) lgkmcnt(0)
	v_mfma_f32_16x16x32_bf16 v[44:47], v[44:47], v[76:79], v[72:75]
	s_nop 2
	ds_read_b128 v[72:75], v0 offset:37632
	s_waitcnt lgkmcnt(0)
	v_mfma_f32_16x16x32_bf16 v[68:71], v[72:75], v[76:79], v[68:71]
	ds_read_b128 v[72:75], v0 offset:41984
	s_waitcnt lgkmcnt(0)
	v_mfma_f32_16x16x32_bf16 v[64:67], v[72:75], v[76:79], v[64:67]
	ds_read_b128 v[72:75], v0 offset:46336
	s_waitcnt lgkmcnt(0)
	v_mfma_f32_16x16x32_bf16 v[60:63], v[72:75], v[76:79], v[60:63]
	ds_read_b128 v[72:75], v0 offset:50688
	s_waitcnt lgkmcnt(0)
	v_mfma_f32_16x16x32_bf16 v[56:59], v[72:75], v[76:79], v[56:59]
	ds_read_b128 v[72:75], v0 offset:55040
	s_waitcnt lgkmcnt(0)
	v_mfma_f32_16x16x32_bf16 v[52:55], v[72:75], v[76:79], v[52:55]
	ds_read_b128 v[72:75], v0 offset:59392
	s_waitcnt lgkmcnt(0)
	v_mfma_f32_16x16x32_bf16 v[48:51], v[72:75], v[76:79], v[48:51]
	ds_read_b128 v[72:75], v0 offset:63744
	v_add_u32_e32 v0, v179, v180
	s_waitcnt lgkmcnt(0)
	v_mfma_f32_16x16x32_bf16 v[40:43], v[72:75], v[76:79], v[40:43]
	ds_read_b128 v[72:75], v0 offset:33280
	v_add_u32_e32 v0, v179, v181
	s_waitcnt lgkmcnt(0)
	v_mfma_f32_16x16x32_bf16 v[36:39], v[72:75], v[76:79], v[36:39]
	ds_read_b128 v[72:75], v0 offset:33280
	v_add_u32_e32 v0, v179, v182
	s_waitcnt lgkmcnt(0)
	v_mfma_f32_16x16x32_bf16 v[32:35], v[72:75], v[76:79], v[32:35]
	ds_read_b128 v[72:75], v0 offset:33280
	v_add_u32_e32 v0, v179, v183
	s_waitcnt lgkmcnt(0)
	v_mfma_f32_16x16x32_bf16 v[28:31], v[72:75], v[76:79], v[28:31]
	ds_read_b128 v[72:75], v0 offset:33280
	v_add_u32_e32 v0, v179, v184
	s_waitcnt lgkmcnt(0)
	v_mfma_f32_16x16x32_bf16 v[24:27], v[72:75], v[76:79], v[24:27]
	ds_read_b128 v[72:75], v0 offset:33280
	v_add_u32_e32 v0, v179, v185
	s_waitcnt lgkmcnt(0)
	v_mfma_f32_16x16x32_bf16 v[20:23], v[72:75], v[76:79], v[20:23]
	ds_read_b128 v[72:75], v0 offset:33280
	v_add_u32_e32 v0, v179, v186
	s_waitcnt lgkmcnt(0)
	v_mfma_f32_16x16x32_bf16 v[16:19], v[72:75], v[76:79], v[16:19]
	ds_read_b128 v[72:75], v0 offset:33280
	v_add_u32_e32 v0, v179, v187
	s_waitcnt lgkmcnt(0)
	v_mfma_f32_16x16x32_bf16 v[12:15], v[72:75], v[76:79], v[12:15]
	ds_read_b128 v[72:75], v0 offset:33280
	v_add_u32_e32 v0, v188, v162
	s_waitcnt lgkmcnt(0)
	v_mfma_f32_16x16x32_bf16 v[8:11], v[72:75], v[76:79], v[8:11]
	global_load_dwordx4 v[76:79], v[134:135], off offset:64
	ds_read_b128 v[72:75], v0 offset:33280
	s_waitcnt vmcnt(0) lgkmcnt(0)
	v_mfma_f32_16x16x32_bf16 v[72:75], v[72:75], v[76:79], v[44:47]
	s_nop 2
	ds_read_b128 v[44:47], v0 offset:37632
	s_waitcnt lgkmcnt(0)
	v_mfma_f32_16x16x32_bf16 v[68:71], v[44:47], v[76:79], v[68:71]
	ds_read_b128 v[44:47], v0 offset:41984
	s_waitcnt lgkmcnt(0)
	v_mfma_f32_16x16x32_bf16 v[64:67], v[44:47], v[76:79], v[64:67]
	ds_read_b128 v[44:47], v0 offset:46336
	s_waitcnt lgkmcnt(0)
	v_mfma_f32_16x16x32_bf16 v[60:63], v[44:47], v[76:79], v[60:63]
	ds_read_b128 v[44:47], v0 offset:50688
	s_waitcnt lgkmcnt(0)
	v_mfma_f32_16x16x32_bf16 v[56:59], v[44:47], v[76:79], v[56:59]
	ds_read_b128 v[44:47], v0 offset:55040
	s_waitcnt lgkmcnt(0)
	v_mfma_f32_16x16x32_bf16 v[52:55], v[44:47], v[76:79], v[52:55]
	ds_read_b128 v[44:47], v0 offset:59392
	s_waitcnt lgkmcnt(0)
	v_mfma_f32_16x16x32_bf16 v[44:47], v[44:47], v[76:79], v[48:51]
	s_nop 2
	ds_read_b128 v[48:51], v0 offset:63744
	v_add_u32_e32 v0, v188, v180
	s_waitcnt lgkmcnt(0)
	v_mfma_f32_16x16x32_bf16 v[40:43], v[48:51], v[76:79], v[40:43]
	ds_read_b128 v[48:51], v0 offset:33280
	v_add_u32_e32 v0, v188, v181
	s_waitcnt lgkmcnt(0)
	v_mfma_f32_16x16x32_bf16 v[36:39], v[48:51], v[76:79], v[36:39]
	ds_read_b128 v[48:51], v0 offset:33280
	v_add_u32_e32 v0, v188, v182
	s_waitcnt lgkmcnt(0)
	v_mfma_f32_16x16x32_bf16 v[32:35], v[48:51], v[76:79], v[32:35]
	ds_read_b128 v[48:51], v0 offset:33280
	v_add_u32_e32 v0, v188, v183
	s_waitcnt lgkmcnt(0)
	v_mfma_f32_16x16x32_bf16 v[28:31], v[48:51], v[76:79], v[28:31]
	ds_read_b128 v[48:51], v0 offset:33280
	v_add_u32_e32 v0, v188, v184
	s_waitcnt lgkmcnt(0)
	v_mfma_f32_16x16x32_bf16 v[24:27], v[48:51], v[76:79], v[24:27]
	ds_read_b128 v[48:51], v0 offset:33280
	v_add_u32_e32 v0, v188, v185
	s_waitcnt lgkmcnt(0)
	v_mfma_f32_16x16x32_bf16 v[20:23], v[48:51], v[76:79], v[20:23]
	ds_read_b128 v[48:51], v0 offset:33280
	v_add_u32_e32 v0, v188, v186
	s_waitcnt lgkmcnt(0)
	v_mfma_f32_16x16x32_bf16 v[16:19], v[48:51], v[76:79], v[16:19]
	ds_read_b128 v[48:51], v0 offset:33280
	v_add_u32_e32 v0, v188, v187
	s_waitcnt lgkmcnt(0)
	v_mfma_f32_16x16x32_bf16 v[12:15], v[48:51], v[76:79], v[12:15]
	ds_read_b128 v[48:51], v0 offset:33280
	v_add_u32_e32 v0, v189, v162
	s_waitcnt lgkmcnt(0)
	v_mfma_f32_16x16x32_bf16 v[8:11], v[48:51], v[76:79], v[8:11]
	global_load_dwordx4 v[48:51], v[134:135], off offset:128
	ds_read_b128 v[76:79], v0 offset:33280
	s_waitcnt vmcnt(0) lgkmcnt(0)
	v_mfma_f32_16x16x32_bf16 v[72:75], v[76:79], v[48:51], v[72:75]
	ds_read_b128 v[76:79], v0 offset:37632
	s_waitcnt lgkmcnt(0)
	v_mfma_f32_16x16x32_bf16 v[76:79], v[76:79], v[48:51], v[68:71]
	s_nop 2
	ds_read_b128 v[68:71], v0 offset:41984
	s_waitcnt lgkmcnt(0)
	v_mfma_f32_16x16x32_bf16 v[80:83], v[68:71], v[48:51], v[64:67]
	s_nop 2
	ds_read_b128 v[64:67], v0 offset:46336
	s_waitcnt lgkmcnt(0)
	v_mfma_f32_16x16x32_bf16 v[84:87], v[64:67], v[48:51], v[60:63]
	s_nop 2
	ds_read_b128 v[60:63], v0 offset:50688
	s_waitcnt lgkmcnt(0)
	v_mfma_f32_16x16x32_bf16 v[88:91], v[60:63], v[48:51], v[56:59]
	s_nop 2
	ds_read_b128 v[56:59], v0 offset:55040
	s_waitcnt lgkmcnt(0)
	v_mfma_f32_16x16x32_bf16 v[92:95], v[56:59], v[48:51], v[52:55]
	s_nop 2
	ds_read_b128 v[52:55], v0 offset:59392
	s_waitcnt lgkmcnt(0)
	v_mfma_f32_16x16x32_bf16 v[44:47], v[52:55], v[48:51], v[44:47]
	ds_read_b128 v[52:55], v0 offset:63744
	v_add_u32_e32 v0, v189, v180
	s_waitcnt lgkmcnt(0)
	v_mfma_f32_16x16x32_bf16 v[40:43], v[52:55], v[48:51], v[40:43]
	ds_read_b128 v[52:55], v0 offset:33280
	v_add_u32_e32 v0, v189, v181
	s_waitcnt lgkmcnt(0)
	v_mfma_f32_16x16x32_bf16 v[36:39], v[52:55], v[48:51], v[36:39]
	ds_read_b128 v[52:55], v0 offset:33280
	v_add_u32_e32 v0, v189, v182
	s_waitcnt lgkmcnt(0)
	v_mfma_f32_16x16x32_bf16 v[32:35], v[52:55], v[48:51], v[32:35]
	ds_read_b128 v[52:55], v0 offset:33280
	v_add_u32_e32 v0, v189, v183
	s_waitcnt lgkmcnt(0)
	v_mfma_f32_16x16x32_bf16 v[28:31], v[52:55], v[48:51], v[28:31]
	ds_read_b128 v[52:55], v0 offset:33280
	v_add_u32_e32 v0, v189, v184
	s_waitcnt lgkmcnt(0)
	v_mfma_f32_16x16x32_bf16 v[24:27], v[52:55], v[48:51], v[24:27]
	ds_read_b128 v[52:55], v0 offset:33280
	v_add_u32_e32 v0, v189, v185
	s_waitcnt lgkmcnt(0)
	v_mfma_f32_16x16x32_bf16 v[20:23], v[52:55], v[48:51], v[20:23]
	ds_read_b128 v[52:55], v0 offset:33280
	v_add_u32_e32 v0, v189, v186
	s_waitcnt lgkmcnt(0)
	v_mfma_f32_16x16x32_bf16 v[16:19], v[52:55], v[48:51], v[16:19]
	ds_read_b128 v[52:55], v0 offset:33280
	v_add_u32_e32 v0, v189, v187
	s_waitcnt lgkmcnt(0)
	v_mfma_f32_16x16x32_bf16 v[12:15], v[52:55], v[48:51], v[12:15]
	ds_read_b128 v[52:55], v0 offset:33280
	v_add_u32_e32 v0, v190, v162
	s_waitcnt lgkmcnt(0)
	v_mfma_f32_16x16x32_bf16 v[8:11], v[52:55], v[48:51], v[8:11]
	ds_read_b128 v[48:51], v0 offset:33280
	s_waitcnt lgkmcnt(0)
	v_mfma_f32_16x16x32_bf16 v[68:71], v[48:51], v[96:99], v[72:75]
	ds_read_b128 v[48:51], v0 offset:37632
	s_nop 1
	ds_read_b128 v[72:75], v0 offset:59392
	s_waitcnt lgkmcnt(1)
	v_mfma_f32_16x16x32_bf16 v[64:67], v[48:51], v[96:99], v[76:79]
	ds_read_b128 v[48:51], v0 offset:41984
	s_waitcnt lgkmcnt(1)
	v_mfma_f32_16x16x32_bf16 v[44:47], v[72:75], v[96:99], v[44:47]
	ds_read_b128 v[72:75], v0 offset:63744
	s_waitcnt lgkmcnt(1)
	v_mfma_f32_16x16x32_bf16 v[60:63], v[48:51], v[96:99], v[80:83]
	ds_read_b128 v[48:51], v0 offset:46336
	s_waitcnt lgkmcnt(0)
	v_mfma_f32_16x16x32_bf16 v[56:59], v[48:51], v[96:99], v[84:87]
	ds_read_b128 v[48:51], v0 offset:50688
	s_waitcnt lgkmcnt(0)
	v_mfma_f32_16x16x32_bf16 v[52:55], v[48:51], v[96:99], v[88:91]
	ds_read_b128 v[48:51], v0 offset:55040
	v_add_u32_e32 v0, v190, v180
	v_mfma_f32_16x16x32_bf16 v[40:43], v[72:75], v[96:99], v[40:43]
	ds_read_b128 v[72:75], v0 offset:33280
	v_add_u32_e32 v0, v190, v181
	s_waitcnt lgkmcnt(0)
	v_mfma_f32_16x16x32_bf16 v[36:39], v[72:75], v[96:99], v[36:39]
	ds_read_b128 v[72:75], v0 offset:33280
	v_add_u32_e32 v0, v190, v182
	s_waitcnt lgkmcnt(0)
	v_mfma_f32_16x16x32_bf16 v[32:35], v[72:75], v[96:99], v[32:35]
	ds_read_b128 v[72:75], v0 offset:33280
	v_add_u32_e32 v0, v190, v183
	s_waitcnt lgkmcnt(0)
	v_mfma_f32_16x16x32_bf16 v[28:31], v[72:75], v[96:99], v[28:31]
	ds_read_b128 v[72:75], v0 offset:33280
	v_add_u32_e32 v0, v190, v184
	s_waitcnt lgkmcnt(0)
	v_mfma_f32_16x16x32_bf16 v[24:27], v[72:75], v[96:99], v[24:27]
	ds_read_b128 v[72:75], v0 offset:33280
	v_add_u32_e32 v0, v190, v185
	s_waitcnt lgkmcnt(0)
	v_mfma_f32_16x16x32_bf16 v[20:23], v[72:75], v[96:99], v[20:23]
	ds_read_b128 v[72:75], v0 offset:33280
	v_add_u32_e32 v0, v190, v186
	s_waitcnt lgkmcnt(0)
	v_mfma_f32_16x16x32_bf16 v[16:19], v[72:75], v[96:99], v[16:19]
	ds_read_b128 v[72:75], v0 offset:33280
	v_add_u32_e32 v0, v190, v187
	s_waitcnt lgkmcnt(0)
	v_mfma_f32_16x16x32_bf16 v[12:15], v[72:75], v[96:99], v[12:15]
	ds_read_b128 v[72:75], v0 offset:33280
	v_lshlrev_b32_e32 v0, 13, v148
	v_lshl_add_u64 v[2:3], v[128:129], 0, v[0:1]
	global_load_dwordx2 v[100:101], v[2:3], off
	v_lshlrev_b32_e32 v0, 13, v203
	v_lshl_add_u64 v[2:3], v[128:129], 0, v[0:1]
	v_mfma_f32_16x16x32_bf16 v[48:51], v[48:51], v[96:99], v[92:95]
	v_lshlrev_b32_e32 v0, 13, v202
	s_waitcnt lgkmcnt(0)
	v_mfma_f32_16x16x32_bf16 v[8:11], v[72:75], v[96:99], v[8:11]
	global_load_dwordx2 v[98:99], v[2:3], off
	v_lshl_add_u64 v[2:3], v[128:129], 0, v[0:1]
	v_lshlrev_b32_e32 v0, 13, v201
	global_load_dwordx2 v[96:97], v[2:3], off
	v_lshl_add_u64 v[2:3], v[128:129], 0, v[0:1]
	v_lshlrev_b32_e32 v0, 13, v200
	global_load_dwordx2 v[94:95], v[2:3], off
	v_lshl_add_u64 v[2:3], v[128:129], 0, v[0:1]
	v_lshlrev_b32_e32 v0, 13, v199
	global_load_dwordx2 v[92:93], v[2:3], off
	v_lshl_add_u64 v[2:3], v[128:129], 0, v[0:1]
	v_lshlrev_b32_e32 v0, 13, v198
	global_load_dwordx2 v[90:91], v[2:3], off
	v_lshl_add_u64 v[2:3], v[128:129], 0, v[0:1]
	v_lshlrev_b32_e32 v0, 13, v197
	global_load_dwordx2 v[88:89], v[2:3], off
	v_lshl_add_u64 v[2:3], v[128:129], 0, v[0:1]
	v_lshlrev_b32_e32 v0, 13, v196
	global_load_dwordx2 v[86:87], v[2:3], off
	v_lshl_add_u64 v[2:3], v[128:129], 0, v[0:1]
	v_lshlrev_b32_e32 v0, 13, v195
	global_load_dwordx2 v[84:85], v[2:3], off
	v_lshl_add_u64 v[2:3], v[128:129], 0, v[0:1]
	v_lshlrev_b32_e32 v0, 13, v194
	global_load_dwordx2 v[82:83], v[2:3], off
	v_lshl_add_u64 v[2:3], v[128:129], 0, v[0:1]
	v_lshlrev_b32_e32 v0, 13, v193
	global_load_dwordx2 v[80:81], v[2:3], off
	v_lshl_add_u64 v[2:3], v[128:129], 0, v[0:1]
	v_lshlrev_b32_e32 v0, 13, v123
	global_load_dwordx2 v[78:79], v[2:3], off
	v_lshl_add_u64 v[2:3], v[128:129], 0, v[0:1]
	v_lshlrev_b32_e32 v0, 13, v121
	global_load_dwordx2 v[76:77], v[2:3], off
	v_lshl_add_u64 v[2:3], v[128:129], 0, v[0:1]
	v_lshlrev_b32_e32 v0, 13, v103
	global_load_dwordx2 v[74:75], v[2:3], off
	v_lshl_add_u64 v[2:3], v[128:129], 0, v[0:1]
	v_lshlrev_b32_e32 v0, 13, v102
	global_load_dwordx2 v[72:73], v[2:3], off
	v_lshl_add_u64 v[2:3], v[128:129], 0, v[0:1]
	global_load_dwordx2 v[2:3], v[2:3], off
	s_waitcnt vmcnt(15)
	v_lshlrev_b32_e32 v204, 16, v100
	v_and_b32_e32 v205, 0xffff0000, v100
	v_lshlrev_b32_e32 v206, 16, v101
	v_and_b32_e32 v207, 0xffff0000, v101
	v_fma_f32 v68, v4, v204, v68
	v_fma_f32 v69, v5, v205, v69
	v_fma_f32 v70, v6, v206, v70
	v_fma_f32 v71, v7, v207, v71
	v_mul_f32_e32 v204, 0x3d372713, v68
	v_mul_f32_e32 v205, 0x3d372713, v69
	v_mul_f32_e32 v206, 0x3d372713, v70
	v_mul_f32_e32 v207, 0x3d372713, v71
	v_mul_f32_e32 v204, v68, v204
	v_mul_f32_e32 v205, v69, v205
	v_mul_f32_e32 v206, v70, v206
	v_mul_f32_e32 v207, v71, v207
	v_fma_f32 v204, v68, v204, v68
	v_fma_f32 v205, v69, v205, v69
	v_fma_f32 v206, v70, v206, v70
	v_fma_f32 v207, v71, v207, v71
	v_mul_f32_e32 v204, 0xbfcc422a, v204
	v_mul_f32_e32 v205, 0xbfcc422a, v205
	v_mul_f32_e32 v206, 0xbfcc422a, v206
	v_mul_f32_e32 v207, 0xbfcc422a, v207
	v_mul_f32_e32 v204, 0x3fb8aa3b, v204
	v_mul_f32_e32 v205, 0x3fb8aa3b, v205
	v_mul_f32_e32 v206, 0x3fb8aa3b, v206
	v_mul_f32_e32 v207, 0x3fb8aa3b, v207
	v_exp_f32_e32 v204, v204
	v_exp_f32_e32 v205, v205
	v_exp_f32_e32 v206, v206
	v_exp_f32_e32 v207, v207
	v_add_f32_e32 v204, 1.0, v204
	v_add_f32_e32 v205, 1.0, v205
	v_add_f32_e32 v206, 1.0, v206
	v_add_f32_e32 v207, 1.0, v207
	v_rcp_f32_e32 v204, v204
	v_rcp_f32_e32 v205, v205
	v_rcp_f32_e32 v206, v206
	v_rcp_f32_e32 v207, v207
	v_mul_f32_e32 v204, v68, v204
	v_mul_f32_e32 v205, v69, v205
	v_mul_f32_e32 v206, v70, v206
	v_mul_f32_e32 v207, v71, v207
	v_cvt_pk_bf16_f32 v208, v204, v205
	v_cvt_pk_bf16_f32 v209, v206, v207
	v_lshlrev_b32_e32 v0, 12, v148
	v_lshl_add_u64 v[210:211], v[132:133], 0, v[0:1]
	global_store_dwordx2 v[210:211], v[208:209], off
	s_waitcnt vmcnt(15)
	v_lshlrev_b32_e32 v204, 16, v98
	v_and_b32_e32 v205, 0xffff0000, v98
	v_lshlrev_b32_e32 v206, 16, v99
	v_and_b32_e32 v207, 0xffff0000, v99
	v_fma_f32 v64, v4, v204, v64
	v_fma_f32 v65, v5, v205, v65
	v_fma_f32 v66, v6, v206, v66
	v_fma_f32 v67, v7, v207, v67
	v_mul_f32_e32 v204, 0x3d372713, v64
	v_mul_f32_e32 v205, 0x3d372713, v65
	v_mul_f32_e32 v206, 0x3d372713, v66
	v_mul_f32_e32 v207, 0x3d372713, v67
	v_mul_f32_e32 v204, v64, v204
	v_mul_f32_e32 v205, v65, v205
	v_mul_f32_e32 v206, v66, v206
	v_mul_f32_e32 v207, v67, v207
	v_fma_f32 v204, v64, v204, v64
	v_fma_f32 v205, v65, v205, v65
	v_fma_f32 v206, v66, v206, v66
	v_fma_f32 v207, v67, v207, v67
	v_mul_f32_e32 v204, 0xbfcc422a, v204
	v_mul_f32_e32 v205, 0xbfcc422a, v205
	v_mul_f32_e32 v206, 0xbfcc422a, v206
	v_mul_f32_e32 v207, 0xbfcc422a, v207
	v_mul_f32_e32 v204, 0x3fb8aa3b, v204
	v_mul_f32_e32 v205, 0x3fb8aa3b, v205
	v_mul_f32_e32 v206, 0x3fb8aa3b, v206
	v_mul_f32_e32 v207, 0x3fb8aa3b, v207
	v_exp_f32_e32 v204, v204
	v_exp_f32_e32 v205, v205
	v_exp_f32_e32 v206, v206
	v_exp_f32_e32 v207, v207
	v_add_f32_e32 v204, 1.0, v204
	v_add_f32_e32 v205, 1.0, v205
	v_add_f32_e32 v206, 1.0, v206
	v_add_f32_e32 v207, 1.0, v207
	v_rcp_f32_e32 v204, v204
	v_rcp_f32_e32 v205, v205
	v_rcp_f32_e32 v206, v206
	v_rcp_f32_e32 v207, v207
	v_mul_f32_e32 v204, v64, v204
	v_mul_f32_e32 v205, v65, v205
	v_mul_f32_e32 v206, v66, v206
	v_mul_f32_e32 v207, v67, v207
	v_cvt_pk_bf16_f32 v208, v204, v205
	v_cvt_pk_bf16_f32 v209, v206, v207
	v_lshlrev_b32_e32 v0, 12, v203
	v_lshl_add_u64 v[210:211], v[132:133], 0, v[0:1]
	global_store_dwordx2 v[210:211], v[208:209], off
	s_waitcnt vmcnt(15)
	v_lshlrev_b32_e32 v204, 16, v96
	v_and_b32_e32 v205, 0xffff0000, v96
	v_lshlrev_b32_e32 v206, 16, v97
	v_and_b32_e32 v207, 0xffff0000, v97
	v_fma_f32 v60, v4, v204, v60
	v_fma_f32 v61, v5, v205, v61
	v_fma_f32 v62, v6, v206, v62
	v_fma_f32 v63, v7, v207, v63
	v_mul_f32_e32 v204, 0x3d372713, v60
	v_mul_f32_e32 v205, 0x3d372713, v61
	v_mul_f32_e32 v206, 0x3d372713, v62
	v_mul_f32_e32 v207, 0x3d372713, v63
	v_mul_f32_e32 v204, v60, v204
	v_mul_f32_e32 v205, v61, v205
	v_mul_f32_e32 v206, v62, v206
	v_mul_f32_e32 v207, v63, v207
	v_fma_f32 v204, v60, v204, v60
	v_fma_f32 v205, v61, v205, v61
	v_fma_f32 v206, v62, v206, v62
	v_fma_f32 v207, v63, v207, v63
	v_mul_f32_e32 v204, 0xbfcc422a, v204
	v_mul_f32_e32 v205, 0xbfcc422a, v205
	v_mul_f32_e32 v206, 0xbfcc422a, v206
	v_mul_f32_e32 v207, 0xbfcc422a, v207
	v_mul_f32_e32 v204, 0x3fb8aa3b, v204
	v_mul_f32_e32 v205, 0x3fb8aa3b, v205
	v_mul_f32_e32 v206, 0x3fb8aa3b, v206
	v_mul_f32_e32 v207, 0x3fb8aa3b, v207
	v_exp_f32_e32 v204, v204
	v_exp_f32_e32 v205, v205
	v_exp_f32_e32 v206, v206
	v_exp_f32_e32 v207, v207
	v_add_f32_e32 v204, 1.0, v204
	v_add_f32_e32 v205, 1.0, v205
	v_add_f32_e32 v206, 1.0, v206
	v_add_f32_e32 v207, 1.0, v207
	v_rcp_f32_e32 v204, v204
	v_rcp_f32_e32 v205, v205
	v_rcp_f32_e32 v206, v206
	v_rcp_f32_e32 v207, v207
	v_mul_f32_e32 v204, v60, v204
	v_mul_f32_e32 v205, v61, v205
	v_mul_f32_e32 v206, v62, v206
	v_mul_f32_e32 v207, v63, v207
	v_cvt_pk_bf16_f32 v208, v204, v205
	v_cvt_pk_bf16_f32 v209, v206, v207
	v_lshlrev_b32_e32 v0, 12, v202
	v_lshl_add_u64 v[210:211], v[132:133], 0, v[0:1]
	global_store_dwordx2 v[210:211], v[208:209], off
	s_waitcnt vmcnt(15)
	v_lshlrev_b32_e32 v204, 16, v94
	v_and_b32_e32 v205, 0xffff0000, v94
	v_lshlrev_b32_e32 v206, 16, v95
	v_and_b32_e32 v207, 0xffff0000, v95
	v_fma_f32 v56, v4, v204, v56
	v_fma_f32 v57, v5, v205, v57
	v_fma_f32 v58, v6, v206, v58
	v_fma_f32 v59, v7, v207, v59
	v_mul_f32_e32 v204, 0x3d372713, v56
	v_mul_f32_e32 v205, 0x3d372713, v57
	v_mul_f32_e32 v206, 0x3d372713, v58
	v_mul_f32_e32 v207, 0x3d372713, v59
	v_mul_f32_e32 v204, v56, v204
	v_mul_f32_e32 v205, v57, v205
	v_mul_f32_e32 v206, v58, v206
	v_mul_f32_e32 v207, v59, v207
	v_fma_f32 v204, v56, v204, v56
	v_fma_f32 v205, v57, v205, v57
	v_fma_f32 v206, v58, v206, v58
	v_fma_f32 v207, v59, v207, v59
	v_mul_f32_e32 v204, 0xbfcc422a, v204
	v_mul_f32_e32 v205, 0xbfcc422a, v205
	v_mul_f32_e32 v206, 0xbfcc422a, v206
	v_mul_f32_e32 v207, 0xbfcc422a, v207
	v_mul_f32_e32 v204, 0x3fb8aa3b, v204
	v_mul_f32_e32 v205, 0x3fb8aa3b, v205
	v_mul_f32_e32 v206, 0x3fb8aa3b, v206
	v_mul_f32_e32 v207, 0x3fb8aa3b, v207
	v_exp_f32_e32 v204, v204
	v_exp_f32_e32 v205, v205
	v_exp_f32_e32 v206, v206
	v_exp_f32_e32 v207, v207
	v_add_f32_e32 v204, 1.0, v204
	v_add_f32_e32 v205, 1.0, v205
	v_add_f32_e32 v206, 1.0, v206
	v_add_f32_e32 v207, 1.0, v207
	v_rcp_f32_e32 v204, v204
	v_rcp_f32_e32 v205, v205
	v_rcp_f32_e32 v206, v206
	v_rcp_f32_e32 v207, v207
	v_mul_f32_e32 v204, v56, v204
	v_mul_f32_e32 v205, v57, v205
	v_mul_f32_e32 v206, v58, v206
	v_mul_f32_e32 v207, v59, v207
	v_cvt_pk_bf16_f32 v208, v204, v205
	v_cvt_pk_bf16_f32 v209, v206, v207
	v_lshlrev_b32_e32 v0, 12, v201
	v_lshl_add_u64 v[210:211], v[132:133], 0, v[0:1]
	global_store_dwordx2 v[210:211], v[208:209], off
	s_waitcnt vmcnt(15)
	v_lshlrev_b32_e32 v204, 16, v92
	v_and_b32_e32 v205, 0xffff0000, v92
	v_lshlrev_b32_e32 v206, 16, v93
	v_and_b32_e32 v207, 0xffff0000, v93
	v_fma_f32 v52, v4, v204, v52
	v_fma_f32 v53, v5, v205, v53
	v_fma_f32 v54, v6, v206, v54
	v_fma_f32 v55, v7, v207, v55
	v_mul_f32_e32 v204, 0x3d372713, v52
	v_mul_f32_e32 v205, 0x3d372713, v53
	v_mul_f32_e32 v206, 0x3d372713, v54
	v_mul_f32_e32 v207, 0x3d372713, v55
	v_mul_f32_e32 v204, v52, v204
	v_mul_f32_e32 v205, v53, v205
	v_mul_f32_e32 v206, v54, v206
	v_mul_f32_e32 v207, v55, v207
	v_fma_f32 v204, v52, v204, v52
	v_fma_f32 v205, v53, v205, v53
	v_fma_f32 v206, v54, v206, v54
	v_fma_f32 v207, v55, v207, v55
	v_mul_f32_e32 v204, 0xbfcc422a, v204
	v_mul_f32_e32 v205, 0xbfcc422a, v205
	v_mul_f32_e32 v206, 0xbfcc422a, v206
	v_mul_f32_e32 v207, 0xbfcc422a, v207
	v_mul_f32_e32 v204, 0x3fb8aa3b, v204
	v_mul_f32_e32 v205, 0x3fb8aa3b, v205
	v_mul_f32_e32 v206, 0x3fb8aa3b, v206
	v_mul_f32_e32 v207, 0x3fb8aa3b, v207
	v_exp_f32_e32 v204, v204
	v_exp_f32_e32 v205, v205
	v_exp_f32_e32 v206, v206
	v_exp_f32_e32 v207, v207
	v_add_f32_e32 v204, 1.0, v204
	v_add_f32_e32 v205, 1.0, v205
	v_add_f32_e32 v206, 1.0, v206
	v_add_f32_e32 v207, 1.0, v207
	v_rcp_f32_e32 v204, v204
	v_rcp_f32_e32 v205, v205
	v_rcp_f32_e32 v206, v206
	v_rcp_f32_e32 v207, v207
	v_mul_f32_e32 v204, v52, v204
	v_mul_f32_e32 v205, v53, v205
	v_mul_f32_e32 v206, v54, v206
	v_mul_f32_e32 v207, v55, v207
	v_cvt_pk_bf16_f32 v208, v204, v205
	v_cvt_pk_bf16_f32 v209, v206, v207
	v_lshlrev_b32_e32 v0, 12, v200
	v_lshl_add_u64 v[210:211], v[132:133], 0, v[0:1]
	global_store_dwordx2 v[210:211], v[208:209], off
	s_waitcnt vmcnt(15)
	v_lshlrev_b32_e32 v204, 16, v90
	v_and_b32_e32 v205, 0xffff0000, v90
	v_lshlrev_b32_e32 v206, 16, v91
	v_and_b32_e32 v207, 0xffff0000, v91
	v_fma_f32 v48, v4, v204, v48
	v_fma_f32 v49, v5, v205, v49
	v_fma_f32 v50, v6, v206, v50
	v_fma_f32 v51, v7, v207, v51
	v_mul_f32_e32 v204, 0x3d372713, v48
	v_mul_f32_e32 v205, 0x3d372713, v49
	v_mul_f32_e32 v206, 0x3d372713, v50
	v_mul_f32_e32 v207, 0x3d372713, v51
	v_mul_f32_e32 v204, v48, v204
	v_mul_f32_e32 v205, v49, v205
	v_mul_f32_e32 v206, v50, v206
	v_mul_f32_e32 v207, v51, v207
	v_fma_f32 v204, v48, v204, v48
	v_fma_f32 v205, v49, v205, v49
	v_fma_f32 v206, v50, v206, v50
	v_fma_f32 v207, v51, v207, v51
	v_mul_f32_e32 v204, 0xbfcc422a, v204
	v_mul_f32_e32 v205, 0xbfcc422a, v205
	v_mul_f32_e32 v206, 0xbfcc422a, v206
	v_mul_f32_e32 v207, 0xbfcc422a, v207
	v_mul_f32_e32 v204, 0x3fb8aa3b, v204
	v_mul_f32_e32 v205, 0x3fb8aa3b, v205
	v_mul_f32_e32 v206, 0x3fb8aa3b, v206
	v_mul_f32_e32 v207, 0x3fb8aa3b, v207
	v_exp_f32_e32 v204, v204
	v_exp_f32_e32 v205, v205
	v_exp_f32_e32 v206, v206
	v_exp_f32_e32 v207, v207
	v_add_f32_e32 v204, 1.0, v204
	v_add_f32_e32 v205, 1.0, v205
	v_add_f32_e32 v206, 1.0, v206
	v_add_f32_e32 v207, 1.0, v207
	v_rcp_f32_e32 v204, v204
	v_rcp_f32_e32 v205, v205
	v_rcp_f32_e32 v206, v206
	v_rcp_f32_e32 v207, v207
	v_mul_f32_e32 v204, v48, v204
	v_mul_f32_e32 v205, v49, v205
	v_mul_f32_e32 v206, v50, v206
	v_mul_f32_e32 v207, v51, v207
	v_cvt_pk_bf16_f32 v208, v204, v205
	v_cvt_pk_bf16_f32 v209, v206, v207
	v_lshlrev_b32_e32 v0, 12, v199
	v_lshl_add_u64 v[210:211], v[132:133], 0, v[0:1]
	global_store_dwordx2 v[210:211], v[208:209], off
	s_waitcnt vmcnt(15)
	v_lshlrev_b32_e32 v204, 16, v88
	v_and_b32_e32 v205, 0xffff0000, v88
	v_lshlrev_b32_e32 v206, 16, v89
	v_and_b32_e32 v207, 0xffff0000, v89
	v_fma_f32 v44, v4, v204, v44
	v_fma_f32 v45, v5, v205, v45
	v_fma_f32 v46, v6, v206, v46
	v_fma_f32 v47, v7, v207, v47
	v_mul_f32_e32 v204, 0x3d372713, v44
	v_mul_f32_e32 v205, 0x3d372713, v45
	v_mul_f32_e32 v206, 0x3d372713, v46
	v_mul_f32_e32 v207, 0x3d372713, v47
	v_mul_f32_e32 v204, v44, v204
	v_mul_f32_e32 v205, v45, v205
	v_mul_f32_e32 v206, v46, v206
	v_mul_f32_e32 v207, v47, v207
	v_fma_f32 v204, v44, v204, v44
	v_fma_f32 v205, v45, v205, v45
	v_fma_f32 v206, v46, v206, v46
	v_fma_f32 v207, v47, v207, v47
	v_mul_f32_e32 v204, 0xbfcc422a, v204
	v_mul_f32_e32 v205, 0xbfcc422a, v205
	v_mul_f32_e32 v206, 0xbfcc422a, v206
	v_mul_f32_e32 v207, 0xbfcc422a, v207
	v_mul_f32_e32 v204, 0x3fb8aa3b, v204
	v_mul_f32_e32 v205, 0x3fb8aa3b, v205
	v_mul_f32_e32 v206, 0x3fb8aa3b, v206
	v_mul_f32_e32 v207, 0x3fb8aa3b, v207
	v_exp_f32_e32 v204, v204
	v_exp_f32_e32 v205, v205
	v_exp_f32_e32 v206, v206
	v_exp_f32_e32 v207, v207
	v_add_f32_e32 v204, 1.0, v204
	v_add_f32_e32 v205, 1.0, v205
	v_add_f32_e32 v206, 1.0, v206
	v_add_f32_e32 v207, 1.0, v207
	v_rcp_f32_e32 v204, v204
	v_rcp_f32_e32 v205, v205
	v_rcp_f32_e32 v206, v206
	v_rcp_f32_e32 v207, v207
	v_mul_f32_e32 v204, v44, v204
	v_mul_f32_e32 v205, v45, v205
	v_mul_f32_e32 v206, v46, v206
	v_mul_f32_e32 v207, v47, v207
	v_cvt_pk_bf16_f32 v208, v204, v205
	v_cvt_pk_bf16_f32 v209, v206, v207
	v_lshlrev_b32_e32 v0, 12, v198
	v_lshl_add_u64 v[210:211], v[132:133], 0, v[0:1]
	global_store_dwordx2 v[210:211], v[208:209], off
	s_waitcnt vmcnt(15)
	v_lshlrev_b32_e32 v204, 16, v86
	v_and_b32_e32 v205, 0xffff0000, v86
	v_lshlrev_b32_e32 v206, 16, v87
	v_and_b32_e32 v207, 0xffff0000, v87
	v_fma_f32 v40, v4, v204, v40
	v_fma_f32 v41, v5, v205, v41
	v_fma_f32 v42, v6, v206, v42
	v_fma_f32 v43, v7, v207, v43
	v_mul_f32_e32 v204, 0x3d372713, v40
	v_mul_f32_e32 v205, 0x3d372713, v41
	v_mul_f32_e32 v206, 0x3d372713, v42
	v_mul_f32_e32 v207, 0x3d372713, v43
	v_mul_f32_e32 v204, v40, v204
	v_mul_f32_e32 v205, v41, v205
	v_mul_f32_e32 v206, v42, v206
	v_mul_f32_e32 v207, v43, v207
	v_fma_f32 v204, v40, v204, v40
	v_fma_f32 v205, v41, v205, v41
	v_fma_f32 v206, v42, v206, v42
	v_fma_f32 v207, v43, v207, v43
	v_mul_f32_e32 v204, 0xbfcc422a, v204
	v_mul_f32_e32 v205, 0xbfcc422a, v205
	v_mul_f32_e32 v206, 0xbfcc422a, v206
	v_mul_f32_e32 v207, 0xbfcc422a, v207
	v_mul_f32_e32 v204, 0x3fb8aa3b, v204
	v_mul_f32_e32 v205, 0x3fb8aa3b, v205
	v_mul_f32_e32 v206, 0x3fb8aa3b, v206
	v_mul_f32_e32 v207, 0x3fb8aa3b, v207
	v_exp_f32_e32 v204, v204
	v_exp_f32_e32 v205, v205
	v_exp_f32_e32 v206, v206
	v_exp_f32_e32 v207, v207
	v_add_f32_e32 v204, 1.0, v204
	v_add_f32_e32 v205, 1.0, v205
	v_add_f32_e32 v206, 1.0, v206
	v_add_f32_e32 v207, 1.0, v207
	v_rcp_f32_e32 v204, v204
	v_rcp_f32_e32 v205, v205
	v_rcp_f32_e32 v206, v206
	v_rcp_f32_e32 v207, v207
	v_mul_f32_e32 v204, v40, v204
	v_mul_f32_e32 v205, v41, v205
	v_mul_f32_e32 v206, v42, v206
	v_mul_f32_e32 v207, v43, v207
	v_cvt_pk_bf16_f32 v208, v204, v205
	v_cvt_pk_bf16_f32 v209, v206, v207
	v_lshlrev_b32_e32 v0, 12, v197
	v_lshl_add_u64 v[210:211], v[132:133], 0, v[0:1]
	global_store_dwordx2 v[210:211], v[208:209], off
	s_waitcnt vmcnt(15)
	v_lshlrev_b32_e32 v204, 16, v84
	v_and_b32_e32 v205, 0xffff0000, v84
	v_lshlrev_b32_e32 v206, 16, v85
	v_and_b32_e32 v207, 0xffff0000, v85
	v_fma_f32 v36, v4, v204, v36
	v_fma_f32 v37, v5, v205, v37
	v_fma_f32 v38, v6, v206, v38
	v_fma_f32 v39, v7, v207, v39
	v_mul_f32_e32 v204, 0x3d372713, v36
	v_mul_f32_e32 v205, 0x3d372713, v37
	v_mul_f32_e32 v206, 0x3d372713, v38
	v_mul_f32_e32 v207, 0x3d372713, v39
	v_mul_f32_e32 v204, v36, v204
	v_mul_f32_e32 v205, v37, v205
	v_mul_f32_e32 v206, v38, v206
	v_mul_f32_e32 v207, v39, v207
	v_fma_f32 v204, v36, v204, v36
	v_fma_f32 v205, v37, v205, v37
	v_fma_f32 v206, v38, v206, v38
	v_fma_f32 v207, v39, v207, v39
	v_mul_f32_e32 v204, 0xbfcc422a, v204
	v_mul_f32_e32 v205, 0xbfcc422a, v205
	v_mul_f32_e32 v206, 0xbfcc422a, v206
	v_mul_f32_e32 v207, 0xbfcc422a, v207
	v_mul_f32_e32 v204, 0x3fb8aa3b, v204
	v_mul_f32_e32 v205, 0x3fb8aa3b, v205
	v_mul_f32_e32 v206, 0x3fb8aa3b, v206
	v_mul_f32_e32 v207, 0x3fb8aa3b, v207
	v_exp_f32_e32 v204, v204
	v_exp_f32_e32 v205, v205
	v_exp_f32_e32 v206, v206
	v_exp_f32_e32 v207, v207
	v_add_f32_e32 v204, 1.0, v204
	v_add_f32_e32 v205, 1.0, v205
	v_add_f32_e32 v206, 1.0, v206
	v_add_f32_e32 v207, 1.0, v207
	v_rcp_f32_e32 v204, v204
	v_rcp_f32_e32 v205, v205
	v_rcp_f32_e32 v206, v206
	v_rcp_f32_e32 v207, v207
	v_mul_f32_e32 v204, v36, v204
	v_mul_f32_e32 v205, v37, v205
	v_mul_f32_e32 v206, v38, v206
	v_mul_f32_e32 v207, v39, v207
	v_cvt_pk_bf16_f32 v208, v204, v205
	v_cvt_pk_bf16_f32 v209, v206, v207
	v_lshlrev_b32_e32 v0, 12, v196
	v_lshl_add_u64 v[210:211], v[132:133], 0, v[0:1]
	global_store_dwordx2 v[210:211], v[208:209], off
	s_waitcnt vmcnt(15)
	v_lshlrev_b32_e32 v204, 16, v82
	v_and_b32_e32 v205, 0xffff0000, v82
	v_lshlrev_b32_e32 v206, 16, v83
	v_and_b32_e32 v207, 0xffff0000, v83
	v_fma_f32 v32, v4, v204, v32
	v_fma_f32 v33, v5, v205, v33
	v_fma_f32 v34, v6, v206, v34
	v_fma_f32 v35, v7, v207, v35
	v_mul_f32_e32 v204, 0x3d372713, v32
	v_mul_f32_e32 v205, 0x3d372713, v33
	v_mul_f32_e32 v206, 0x3d372713, v34
	v_mul_f32_e32 v207, 0x3d372713, v35
	v_mul_f32_e32 v204, v32, v204
	v_mul_f32_e32 v205, v33, v205
	v_mul_f32_e32 v206, v34, v206
	v_mul_f32_e32 v207, v35, v207
	v_fma_f32 v204, v32, v204, v32
	v_fma_f32 v205, v33, v205, v33
	v_fma_f32 v206, v34, v206, v34
	v_fma_f32 v207, v35, v207, v35
	v_mul_f32_e32 v204, 0xbfcc422a, v204
	v_mul_f32_e32 v205, 0xbfcc422a, v205
	v_mul_f32_e32 v206, 0xbfcc422a, v206
	v_mul_f32_e32 v207, 0xbfcc422a, v207
	v_mul_f32_e32 v204, 0x3fb8aa3b, v204
	v_mul_f32_e32 v205, 0x3fb8aa3b, v205
	v_mul_f32_e32 v206, 0x3fb8aa3b, v206
	v_mul_f32_e32 v207, 0x3fb8aa3b, v207
	v_exp_f32_e32 v204, v204
	v_exp_f32_e32 v205, v205
	v_exp_f32_e32 v206, v206
	v_exp_f32_e32 v207, v207
	v_add_f32_e32 v204, 1.0, v204
	v_add_f32_e32 v205, 1.0, v205
	v_add_f32_e32 v206, 1.0, v206
	v_add_f32_e32 v207, 1.0, v207
	v_rcp_f32_e32 v204, v204
	v_rcp_f32_e32 v205, v205
	v_rcp_f32_e32 v206, v206
	v_rcp_f32_e32 v207, v207
	v_mul_f32_e32 v204, v32, v204
	v_mul_f32_e32 v205, v33, v205
	v_mul_f32_e32 v206, v34, v206
	v_mul_f32_e32 v207, v35, v207
	v_cvt_pk_bf16_f32 v208, v204, v205
	v_cvt_pk_bf16_f32 v209, v206, v207
	v_lshlrev_b32_e32 v0, 12, v195
	v_lshl_add_u64 v[210:211], v[132:133], 0, v[0:1]
	global_store_dwordx2 v[210:211], v[208:209], off
	s_waitcnt vmcnt(15)
	v_lshlrev_b32_e32 v204, 16, v80
	v_and_b32_e32 v205, 0xffff0000, v80
	v_lshlrev_b32_e32 v206, 16, v81
	v_and_b32_e32 v207, 0xffff0000, v81
	v_fma_f32 v28, v4, v204, v28
	v_fma_f32 v29, v5, v205, v29
	v_fma_f32 v30, v6, v206, v30
	v_fma_f32 v31, v7, v207, v31
	v_mul_f32_e32 v204, 0x3d372713, v28
	v_mul_f32_e32 v205, 0x3d372713, v29
	v_mul_f32_e32 v206, 0x3d372713, v30
	v_mul_f32_e32 v207, 0x3d372713, v31
	v_mul_f32_e32 v204, v28, v204
	v_mul_f32_e32 v205, v29, v205
	v_mul_f32_e32 v206, v30, v206
	v_mul_f32_e32 v207, v31, v207
	v_fma_f32 v204, v28, v204, v28
	v_fma_f32 v205, v29, v205, v29
	v_fma_f32 v206, v30, v206, v30
	v_fma_f32 v207, v31, v207, v31
	v_mul_f32_e32 v204, 0xbfcc422a, v204
	v_mul_f32_e32 v205, 0xbfcc422a, v205
	v_mul_f32_e32 v206, 0xbfcc422a, v206
	v_mul_f32_e32 v207, 0xbfcc422a, v207
	v_mul_f32_e32 v204, 0x3fb8aa3b, v204
	v_mul_f32_e32 v205, 0x3fb8aa3b, v205
	v_mul_f32_e32 v206, 0x3fb8aa3b, v206
	v_mul_f32_e32 v207, 0x3fb8aa3b, v207
	v_exp_f32_e32 v204, v204
	v_exp_f32_e32 v205, v205
	v_exp_f32_e32 v206, v206
	v_exp_f32_e32 v207, v207
	v_add_f32_e32 v204, 1.0, v204
	v_add_f32_e32 v205, 1.0, v205
	v_add_f32_e32 v206, 1.0, v206
	v_add_f32_e32 v207, 1.0, v207
	v_rcp_f32_e32 v204, v204
	v_rcp_f32_e32 v205, v205
	v_rcp_f32_e32 v206, v206
	v_rcp_f32_e32 v207, v207
	v_mul_f32_e32 v204, v28, v204
	v_mul_f32_e32 v205, v29, v205
	v_mul_f32_e32 v206, v30, v206
	v_mul_f32_e32 v207, v31, v207
	v_cvt_pk_bf16_f32 v208, v204, v205
	v_cvt_pk_bf16_f32 v209, v206, v207
	v_lshlrev_b32_e32 v0, 12, v194
	v_lshl_add_u64 v[210:211], v[132:133], 0, v[0:1]
	global_store_dwordx2 v[210:211], v[208:209], off
	s_waitcnt vmcnt(15)
	v_lshlrev_b32_e32 v204, 16, v78
	v_and_b32_e32 v205, 0xffff0000, v78
	v_lshlrev_b32_e32 v206, 16, v79
	v_and_b32_e32 v207, 0xffff0000, v79
	v_fma_f32 v24, v4, v204, v24
	v_fma_f32 v25, v5, v205, v25
	v_fma_f32 v26, v6, v206, v26
	v_fma_f32 v27, v7, v207, v27
	v_mul_f32_e32 v204, 0x3d372713, v24
	v_mul_f32_e32 v205, 0x3d372713, v25
	v_mul_f32_e32 v206, 0x3d372713, v26
	v_mul_f32_e32 v207, 0x3d372713, v27
	v_mul_f32_e32 v204, v24, v204
	v_mul_f32_e32 v205, v25, v205
	v_mul_f32_e32 v206, v26, v206
	v_mul_f32_e32 v207, v27, v207
	v_fma_f32 v204, v24, v204, v24
	v_fma_f32 v205, v25, v205, v25
	v_fma_f32 v206, v26, v206, v26
	v_fma_f32 v207, v27, v207, v27
	v_mul_f32_e32 v204, 0xbfcc422a, v204
	v_mul_f32_e32 v205, 0xbfcc422a, v205
	v_mul_f32_e32 v206, 0xbfcc422a, v206
	v_mul_f32_e32 v207, 0xbfcc422a, v207
	v_mul_f32_e32 v204, 0x3fb8aa3b, v204
	v_mul_f32_e32 v205, 0x3fb8aa3b, v205
	v_mul_f32_e32 v206, 0x3fb8aa3b, v206
	v_mul_f32_e32 v207, 0x3fb8aa3b, v207
	v_exp_f32_e32 v204, v204
	v_exp_f32_e32 v205, v205
	v_exp_f32_e32 v206, v206
	v_exp_f32_e32 v207, v207
	v_add_f32_e32 v204, 1.0, v204
	v_add_f32_e32 v205, 1.0, v205
	v_add_f32_e32 v206, 1.0, v206
	v_add_f32_e32 v207, 1.0, v207
	v_rcp_f32_e32 v204, v204
	v_rcp_f32_e32 v205, v205
	v_rcp_f32_e32 v206, v206
	v_rcp_f32_e32 v207, v207
	v_mul_f32_e32 v204, v24, v204
	v_mul_f32_e32 v205, v25, v205
	v_mul_f32_e32 v206, v26, v206
	v_mul_f32_e32 v207, v27, v207
	v_cvt_pk_bf16_f32 v208, v204, v205
	v_cvt_pk_bf16_f32 v209, v206, v207
	v_lshlrev_b32_e32 v0, 12, v193
	v_lshl_add_u64 v[210:211], v[132:133], 0, v[0:1]
	global_store_dwordx2 v[210:211], v[208:209], off
	s_waitcnt vmcnt(15)
	v_lshlrev_b32_e32 v204, 16, v76
	v_and_b32_e32 v205, 0xffff0000, v76
	v_lshlrev_b32_e32 v206, 16, v77
	v_and_b32_e32 v207, 0xffff0000, v77
	v_fma_f32 v20, v4, v204, v20
	v_fma_f32 v21, v5, v205, v21
	v_fma_f32 v22, v6, v206, v22
	v_fma_f32 v23, v7, v207, v23
	v_mul_f32_e32 v204, 0x3d372713, v20
	v_mul_f32_e32 v205, 0x3d372713, v21
	v_mul_f32_e32 v206, 0x3d372713, v22
	v_mul_f32_e32 v207, 0x3d372713, v23
	v_mul_f32_e32 v204, v20, v204
	v_mul_f32_e32 v205, v21, v205
	v_mul_f32_e32 v206, v22, v206
	v_mul_f32_e32 v207, v23, v207
	v_fma_f32 v204, v20, v204, v20
	v_fma_f32 v205, v21, v205, v21
	v_fma_f32 v206, v22, v206, v22
	v_fma_f32 v207, v23, v207, v23
	v_mul_f32_e32 v204, 0xbfcc422a, v204
	v_mul_f32_e32 v205, 0xbfcc422a, v205
	v_mul_f32_e32 v206, 0xbfcc422a, v206
	v_mul_f32_e32 v207, 0xbfcc422a, v207
	v_mul_f32_e32 v204, 0x3fb8aa3b, v204
	v_mul_f32_e32 v205, 0x3fb8aa3b, v205
	v_mul_f32_e32 v206, 0x3fb8aa3b, v206
	v_mul_f32_e32 v207, 0x3fb8aa3b, v207
	v_exp_f32_e32 v204, v204
	v_exp_f32_e32 v205, v205
	v_exp_f32_e32 v206, v206
	v_exp_f32_e32 v207, v207
	v_add_f32_e32 v204, 1.0, v204
	v_add_f32_e32 v205, 1.0, v205
	v_add_f32_e32 v206, 1.0, v206
	v_add_f32_e32 v207, 1.0, v207
	v_rcp_f32_e32 v204, v204
	v_rcp_f32_e32 v205, v205
	v_rcp_f32_e32 v206, v206
	v_rcp_f32_e32 v207, v207
	v_mul_f32_e32 v204, v20, v204
	v_mul_f32_e32 v205, v21, v205
	v_mul_f32_e32 v206, v22, v206
	v_mul_f32_e32 v207, v23, v207
	v_cvt_pk_bf16_f32 v208, v204, v205
	v_cvt_pk_bf16_f32 v209, v206, v207
	v_lshlrev_b32_e32 v0, 12, v123
	v_lshl_add_u64 v[210:211], v[132:133], 0, v[0:1]
	global_store_dwordx2 v[210:211], v[208:209], off
	s_waitcnt vmcnt(15)
	v_lshlrev_b32_e32 v204, 16, v74
	v_and_b32_e32 v205, 0xffff0000, v74
	v_lshlrev_b32_e32 v206, 16, v75
	v_and_b32_e32 v207, 0xffff0000, v75
	v_fma_f32 v16, v4, v204, v16
	v_fma_f32 v17, v5, v205, v17
	v_fma_f32 v18, v6, v206, v18
	v_fma_f32 v19, v7, v207, v19
	v_mul_f32_e32 v204, 0x3d372713, v16
	v_mul_f32_e32 v205, 0x3d372713, v17
	v_mul_f32_e32 v206, 0x3d372713, v18
	v_mul_f32_e32 v207, 0x3d372713, v19
	v_mul_f32_e32 v204, v16, v204
	v_mul_f32_e32 v205, v17, v205
	v_mul_f32_e32 v206, v18, v206
	v_mul_f32_e32 v207, v19, v207
	v_fma_f32 v204, v16, v204, v16
	v_fma_f32 v205, v17, v205, v17
	v_fma_f32 v206, v18, v206, v18
	v_fma_f32 v207, v19, v207, v19
	v_mul_f32_e32 v204, 0xbfcc422a, v204
	v_mul_f32_e32 v205, 0xbfcc422a, v205
	v_mul_f32_e32 v206, 0xbfcc422a, v206
	v_mul_f32_e32 v207, 0xbfcc422a, v207
	v_mul_f32_e32 v204, 0x3fb8aa3b, v204
	v_mul_f32_e32 v205, 0x3fb8aa3b, v205
	v_mul_f32_e32 v206, 0x3fb8aa3b, v206
	v_mul_f32_e32 v207, 0x3fb8aa3b, v207
	v_exp_f32_e32 v204, v204
	v_exp_f32_e32 v205, v205
	v_exp_f32_e32 v206, v206
	v_exp_f32_e32 v207, v207
	v_add_f32_e32 v204, 1.0, v204
	v_add_f32_e32 v205, 1.0, v205
	v_add_f32_e32 v206, 1.0, v206
	v_add_f32_e32 v207, 1.0, v207
	v_rcp_f32_e32 v204, v204
	v_rcp_f32_e32 v205, v205
	v_rcp_f32_e32 v206, v206
	v_rcp_f32_e32 v207, v207
	v_mul_f32_e32 v204, v16, v204
	v_mul_f32_e32 v205, v17, v205
	v_mul_f32_e32 v206, v18, v206
	v_mul_f32_e32 v207, v19, v207
	v_cvt_pk_bf16_f32 v208, v204, v205
	v_cvt_pk_bf16_f32 v209, v206, v207
	v_lshlrev_b32_e32 v0, 12, v121
	v_lshl_add_u64 v[210:211], v[132:133], 0, v[0:1]
	global_store_dwordx2 v[210:211], v[208:209], off
	s_waitcnt vmcnt(15)
	v_lshlrev_b32_e32 v204, 16, v72
	v_and_b32_e32 v205, 0xffff0000, v72
	v_lshlrev_b32_e32 v206, 16, v73
	v_and_b32_e32 v207, 0xffff0000, v73
	v_fma_f32 v12, v4, v204, v12
	v_fma_f32 v13, v5, v205, v13
	v_fma_f32 v14, v6, v206, v14
	v_fma_f32 v15, v7, v207, v15
	v_mul_f32_e32 v204, 0x3d372713, v12
	v_mul_f32_e32 v205, 0x3d372713, v13
	v_mul_f32_e32 v206, 0x3d372713, v14
	v_mul_f32_e32 v207, 0x3d372713, v15
	v_mul_f32_e32 v204, v12, v204
	v_mul_f32_e32 v205, v13, v205
	v_mul_f32_e32 v206, v14, v206
	v_mul_f32_e32 v207, v15, v207
	v_fma_f32 v204, v12, v204, v12
	v_fma_f32 v205, v13, v205, v13
	v_fma_f32 v206, v14, v206, v14
	v_fma_f32 v207, v15, v207, v15
	v_mul_f32_e32 v204, 0xbfcc422a, v204
	v_mul_f32_e32 v205, 0xbfcc422a, v205
	v_mul_f32_e32 v206, 0xbfcc422a, v206
	v_mul_f32_e32 v207, 0xbfcc422a, v207
	v_mul_f32_e32 v204, 0x3fb8aa3b, v204
	v_mul_f32_e32 v205, 0x3fb8aa3b, v205
	v_mul_f32_e32 v206, 0x3fb8aa3b, v206
	v_mul_f32_e32 v207, 0x3fb8aa3b, v207
	v_exp_f32_e32 v204, v204
	v_exp_f32_e32 v205, v205
	v_exp_f32_e32 v206, v206
	v_exp_f32_e32 v207, v207
	v_add_f32_e32 v204, 1.0, v204
	v_add_f32_e32 v205, 1.0, v205
	v_add_f32_e32 v206, 1.0, v206
	v_add_f32_e32 v207, 1.0, v207
	v_rcp_f32_e32 v204, v204
	v_rcp_f32_e32 v205, v205
	v_rcp_f32_e32 v206, v206
	v_rcp_f32_e32 v207, v207
	v_mul_f32_e32 v204, v12, v204
	v_mul_f32_e32 v205, v13, v205
	v_mul_f32_e32 v206, v14, v206
	v_mul_f32_e32 v207, v15, v207
	v_cvt_pk_bf16_f32 v208, v204, v205
	v_cvt_pk_bf16_f32 v209, v206, v207
	v_lshlrev_b32_e32 v0, 12, v103
	v_lshl_add_u64 v[210:211], v[132:133], 0, v[0:1]
	global_store_dwordx2 v[210:211], v[208:209], off
	s_waitcnt vmcnt(15)
	v_lshlrev_b32_e32 v204, 16, v2
	v_and_b32_e32 v205, 0xffff0000, v2
	v_lshlrev_b32_e32 v206, 16, v3
	v_and_b32_e32 v207, 0xffff0000, v3
	v_fma_f32 v8, v4, v204, v8
	v_fma_f32 v9, v5, v205, v9
	v_fma_f32 v10, v6, v206, v10
	v_fma_f32 v11, v7, v207, v11
	v_mul_f32_e32 v204, 0x3d372713, v8
	v_mul_f32_e32 v205, 0x3d372713, v9
	v_mul_f32_e32 v206, 0x3d372713, v10
	v_mul_f32_e32 v207, 0x3d372713, v11
	v_mul_f32_e32 v204, v8, v204
	v_mul_f32_e32 v205, v9, v205
	v_mul_f32_e32 v206, v10, v206
	v_mul_f32_e32 v207, v11, v207
	v_fma_f32 v204, v8, v204, v8
	v_fma_f32 v205, v9, v205, v9
	v_fma_f32 v206, v10, v206, v10
	v_fma_f32 v207, v11, v207, v11
	v_mul_f32_e32 v204, 0xbfcc422a, v204
	v_mul_f32_e32 v205, 0xbfcc422a, v205
	v_mul_f32_e32 v206, 0xbfcc422a, v206
	v_mul_f32_e32 v207, 0xbfcc422a, v207
	v_mul_f32_e32 v204, 0x3fb8aa3b, v204
	v_mul_f32_e32 v205, 0x3fb8aa3b, v205
	v_mul_f32_e32 v206, 0x3fb8aa3b, v206
	v_mul_f32_e32 v207, 0x3fb8aa3b, v207
	v_exp_f32_e32 v204, v204
	v_exp_f32_e32 v205, v205
	v_exp_f32_e32 v206, v206
	v_exp_f32_e32 v207, v207
	v_add_f32_e32 v204, 1.0, v204
	v_add_f32_e32 v205, 1.0, v205
	v_add_f32_e32 v206, 1.0, v206
	v_add_f32_e32 v207, 1.0, v207
	v_rcp_f32_e32 v204, v204
	v_rcp_f32_e32 v205, v205
	v_rcp_f32_e32 v206, v206
	v_rcp_f32_e32 v207, v207
	v_mul_f32_e32 v204, v8, v204
	v_mul_f32_e32 v205, v9, v205
	v_mul_f32_e32 v206, v10, v206
	v_mul_f32_e32 v207, v11, v207
	v_cvt_pk_bf16_f32 v208, v204, v205
	v_cvt_pk_bf16_f32 v209, v206, v207
	v_lshlrev_b32_e32 v0, 12, v102
	v_lshl_add_u64 v[210:211], v[132:133], 0, v[0:1]
	global_store_dwordx2 v[210:211], v[208:209], off
	s_cbranch_scc1 .LBB0_149
